# P1 context workgroups: the 35 modulation-table loads were issued one at a time with a full wait after each (33 dependent round trips on the phase's critical path); now two batches, sums in source orde
# speedup vs baseline: 1.0131x; 1.0050x over previous
.LBB0_189:
	s_and_b64 vcc, exec, s[6:7]
	s_cbranch_vccz .LBB0_220
	s_and_b32 s28, s2, 3
	s_lshl_b32 s3, s28, 6
	s_lshl_b32 s4, s60, 3
	s_add_i32 s8, s4, s3
	s_lshr_b32 s6, s2, 2
	s_mov_b32 s7, 0
	s_ashr_i32 s9, s8, 31
	s_lshl_b64 s[4:5], s[6:7], 20
	s_lshl_b64 s[10:11], s[8:9], 12
	s_add_u32 s3, s56, s4
	s_addc_u32 s4, s57, s5
	s_add_u32 s10, s3, s10
	s_addc_u32 s11, s4, s11
	v_mov_b32_e32 v129, 0
	v_lshlrev_b32_e32 v128, 4, v130
	s_waitcnt vmcnt(1)
	v_lshl_add_u64 v[0:1], s[10:11], 0, v[128:129]
	s_movk_i32 s3, 0x1000
	v_add_co_u32_e32 v2, vcc, s3, v0
	s_movk_i32 s3, 0x2000
	s_nop 0
	v_addc_co_u32_e32 v3, vcc, 0, v1, vcc
	s_waitcnt vmcnt(0)
	v_add_co_u32_e32 v4, vcc, s3, v0
	s_movk_i32 s3, 0x3000
	s_nop 0
	v_addc_co_u32_e32 v5, vcc, 0, v1, vcc
	v_add_co_u32_e32 v6, vcc, s3, v0
	s_movk_i32 s3, 0x4000
	s_nop 0
	v_addc_co_u32_e32 v7, vcc, 0, v1, vcc
	v_add_co_u32_e32 v8, vcc, s3, v0
	s_movk_i32 s3, 0x5000
	s_nop 0
	v_addc_co_u32_e32 v9, vcc, 0, v1, vcc
	global_load_dwordx4 v[104:107], v[2:3], off offset:1024 nt
	global_load_dwordx4 v[96:99], v[2:3], off offset:2048 nt
	global_load_dwordx4 v[108:111], v[4:5], off offset:-4096 nt
	global_load_dwordx4 v[92:95], v[4:5], off nt
	global_load_dwordx4 v[88:91], v[4:5], off offset:1024 nt
	global_load_dwordx4 v[76:79], v[4:5], off offset:2048 nt
	global_load_dwordx4 v[100:103], v[2:3], off offset:3072 nt
	global_load_dwordx4 v[72:75], v[6:7], off offset:1024 nt
	global_load_dwordx4 v[64:67], v[6:7], off offset:2048 nt
	global_load_dwordx4 v[60:63], v[6:7], off offset:3072 nt
	v_add_co_u32_e32 v6, vcc, s3, v0
	s_movk_i32 s3, 0x6000
	s_nop 0
	v_addc_co_u32_e32 v7, vcc, 0, v1, vcc
	v_add_co_u32_e32 v10, vcc, s3, v0
	s_mov_b64 s[4:5], 0x4000
	s_nop 0
	v_addc_co_u32_e32 v11, vcc, 0, v1, vcc
	v_lshl_add_u64 v[2:3], v[0:1], 0, s[4:5]
	v_add_co_u32_e32 v0, vcc, 0x7000, v0
	global_load_dwordx4 v[56:59], v[2:3], off offset:1024 nt
	global_load_dwordx4 v[48:51], v[2:3], off offset:2048 nt
	v_addc_co_u32_e32 v1, vcc, 0, v1, vcc
	global_load_dwordx4 v[44:47], v[2:3], off offset:3072 nt
	global_load_dwordx4 v[40:43], v[6:7], off offset:1024 nt
	global_load_dwordx4 v[36:39], v[6:7], off offset:2048 nt
	global_load_dwordx4 v[32:35], v[6:7], off offset:3072 nt
	global_load_dwordx4 v[84:87], v[4:5], off offset:3072 nt
	global_load_dwordx4 v[80:83], v[8:9], off offset:-4096 nt
	global_load_dwordx4 v[68:71], v[8:9], off nt
	global_load_dwordx4 v[52:55], v[10:11], off offset:-4096 nt
	global_load_dwordx4 v[28:31], v[10:11], off nt
	global_load_dwordx4 v[24:27], v[10:11], off offset:1024 nt
	global_load_dwordx4 v[20:23], v[10:11], off offset:2048 nt
	global_load_dwordx4 v[16:19], v[10:11], off offset:3072 nt
	global_load_dwordx4 v[12:15], v[0:1], off nt
	s_nop 0
	global_load_dwordx4 v[8:11], v[0:1], off offset:1024 nt
	global_load_dwordx4 v[4:7], v[0:1], off offset:2048 nt
	s_nop 0
	global_load_dwordx4 v[0:3], v[0:1], off offset:3072 nt
	s_nop 0
	global_load_dwordx4 v[124:127], v128, s[10:11] nt
	global_load_dwordx4 v[120:123], v128, s[10:11] offset:1024 nt
	global_load_dwordx4 v[116:119], v128, s[10:11] offset:2048 nt
	global_load_dwordx4 v[112:115], v128, s[10:11] offset:3072 nt
	s_movk_i32 s3, 0x100
	v_lshlrev_b32_e32 v128, 2, v130
	v_cmp_gt_i32_e32 vcc, s3, v134
	s_and_saveexec_b64 s[10:11], vcc
	s_cbranch_execz .LBB0_192
	v_lshlrev_b32_e32 v130, 2, v134
	v_ashrrev_i32_e32 v131, 31, v130
	v_lshlrev_b64 v[130:131], 2, v[130:131]
	v_lshl_add_u32 v135, v134, 4, 0
	v_lshl_add_u64 v[132:133], s[62:63], 0, v[130:131]
	global_load_dwordx4 v[160:163], v[132:133], off
	s_mov_b32 vcc_hi, 0
	s_mov_b32 vcc_lo, 0x1000
	v_lshl_add_u64 v[136:137], v[132:133], 0, vcc
	global_load_dwordx4 v[164:167], v[136:137], off
	v_lshl_add_u64 v[136:137], s[64:65], 0, v[130:131]
	global_load_dwordx4 v[168:171], v[136:137], off
	v_lshl_add_u64 v[132:133], s[36:37], 0, v[130:131]
	s_mov_b32 vcc_lo, 0x18000
	v_lshl_add_u64 v[136:137], v[132:133], 0, vcc
	global_load_dwordx4 v[172:175], v[136:137], off
	s_mov_b32 vcc_lo, 0x19000
	v_lshl_add_u64 v[136:137], v[132:133], 0, vcc
	global_load_dwordx4 v[176:179], v[136:137], off
	s_mov_b32 vcc_lo, 0x33000
	v_lshl_add_u64 v[136:137], v[132:133], 0, vcc
	global_load_dwordx4 v[180:183], v[136:137], off
	s_mov_b32 vcc_lo, 0x34000
	v_lshl_add_u64 v[136:137], v[132:133], 0, vcc
	global_load_dwordx4 v[184:187], v[136:137], off
	s_mov_b32 vcc_lo, 0x4e000
	v_lshl_add_u64 v[136:137], v[132:133], 0, vcc
	global_load_dwordx4 v[188:191], v[136:137], off
	s_mov_b32 vcc_lo, 0x4f000
	v_lshl_add_u64 v[136:137], v[132:133], 0, vcc
	global_load_dwordx4 v[192:195], v[136:137], off
	s_mov_b32 vcc_lo, 0x69000
	v_lshl_add_u64 v[136:137], v[132:133], 0, vcc
	global_load_dwordx4 v[196:199], v[136:137], off
	s_mov_b32 vcc_lo, 0x6a000
	v_lshl_add_u64 v[136:137], v[132:133], 0, vcc
	global_load_dwordx4 v[200:203], v[136:137], off
	s_mov_b32 vcc_lo, 0x84000
	v_lshl_add_u64 v[136:137], v[132:133], 0, vcc
	global_load_dwordx4 v[204:207], v[136:137], off
	s_mov_b32 vcc_lo, 0x85000
	v_lshl_add_u64 v[136:137], v[132:133], 0, vcc
	global_load_dwordx4 v[208:211], v[136:137], off
	s_mov_b32 vcc_lo, 0x9f000
	v_lshl_add_u64 v[136:137], v[132:133], 0, vcc
	global_load_dwordx4 v[212:215], v[136:137], off
	s_mov_b32 vcc_lo, 0xa0000
	v_lshl_add_u64 v[136:137], v[132:133], 0, vcc
	global_load_dwordx4 v[218:221], v[136:137], off
	s_mov_b32 vcc_lo, 0xba000
	v_lshl_add_u64 v[136:137], v[132:133], 0, vcc
	global_load_dwordx4 v[222:225], v[136:137], off
	s_mov_b32 vcc_lo, 0xbb000
	v_lshl_add_u64 v[136:137], v[132:133], 0, vcc
	global_load_dwordx4 v[226:229], v[136:137], off
	s_mov_b32 vcc_lo, 0xd5000
	v_lshl_add_u64 v[136:137], v[132:133], 0, vcc
	global_load_dwordx4 v[230:233], v[136:137], off
	s_mov_b32 vcc_lo, 0xd6000
	v_lshl_add_u64 v[136:137], v[132:133], 0, vcc
	global_load_dwordx4 v[234:237], v[136:137], off
	s_mov_b32 vcc_lo, 0xf0000
	v_lshl_add_u64 v[136:137], v[132:133], 0, vcc
	global_load_dwordx4 v[238:241], v[136:137], off
	s_mov_b32 vcc_lo, 0xf1000
	v_lshl_add_u64 v[136:137], v[132:133], 0, vcc
	global_load_dwordx4 v[246:249], v[136:137], off
	s_waitcnt vmcnt(0)
	v_pk_add_f32 v[144:145], v[160:161], v[172:173]
	v_pk_add_f32 v[146:147], v[162:163], v[174:175]
	v_pk_add_f32 v[140:141], v[164:165], v[176:177]
	v_pk_add_f32 v[142:143], v[166:167], v[178:179]
	v_pk_add_f32 v[144:145], v[144:145], v[180:181]
	v_pk_add_f32 v[146:147], v[146:147], v[182:183]
	v_pk_add_f32 v[140:141], v[140:141], v[184:185]
	v_pk_add_f32 v[142:143], v[142:143], v[186:187]
	v_pk_add_f32 v[144:145], v[144:145], v[188:189]
	v_pk_add_f32 v[146:147], v[146:147], v[190:191]
	v_pk_add_f32 v[140:141], v[140:141], v[192:193]
	v_pk_add_f32 v[142:143], v[142:143], v[194:195]
	v_pk_add_f32 v[144:145], v[144:145], v[196:197]
	v_pk_add_f32 v[146:147], v[146:147], v[198:199]
	v_pk_add_f32 v[140:141], v[140:141], v[200:201]
	v_pk_add_f32 v[142:143], v[142:143], v[202:203]
	v_pk_add_f32 v[144:145], v[144:145], v[204:205]
	v_pk_add_f32 v[146:147], v[146:147], v[206:207]
	v_pk_add_f32 v[140:141], v[140:141], v[208:209]
	v_pk_add_f32 v[142:143], v[142:143], v[210:211]
	v_pk_add_f32 v[144:145], v[144:145], v[212:213]
	v_pk_add_f32 v[146:147], v[146:147], v[214:215]
	v_pk_add_f32 v[140:141], v[140:141], v[218:219]
	v_pk_add_f32 v[142:143], v[142:143], v[220:221]
	v_pk_add_f32 v[144:145], v[144:145], v[222:223]
	v_pk_add_f32 v[146:147], v[146:147], v[224:225]
	v_pk_add_f32 v[140:141], v[140:141], v[226:227]
	v_pk_add_f32 v[142:143], v[142:143], v[228:229]
	v_pk_add_f32 v[144:145], v[144:145], v[230:231]
	v_pk_add_f32 v[146:147], v[146:147], v[232:233]
	v_pk_add_f32 v[140:141], v[140:141], v[234:235]
	v_pk_add_f32 v[142:143], v[142:143], v[236:237]
	v_pk_add_f32 v[144:145], v[144:145], v[238:239]
	v_pk_add_f32 v[146:147], v[146:147], v[240:241]
	v_pk_add_f32 v[140:141], v[140:141], v[246:247]
	v_pk_add_f32 v[142:143], v[142:143], v[248:249]
	s_mov_b32 vcc_lo, 0x10b000
	v_lshl_add_u64 v[136:137], v[132:133], 0, vcc
	global_load_dwordx4 v[172:175], v[136:137], off
	s_mov_b32 vcc_lo, 0x10c000
	v_lshl_add_u64 v[136:137], v[132:133], 0, vcc
	global_load_dwordx4 v[176:179], v[136:137], off
	s_mov_b32 vcc_lo, 0x126000
	v_lshl_add_u64 v[136:137], v[132:133], 0, vcc
	global_load_dwordx4 v[180:183], v[136:137], off
	s_mov_b32 vcc_lo, 0x127000
	v_lshl_add_u64 v[136:137], v[132:133], 0, vcc
	global_load_dwordx4 v[184:187], v[136:137], off
	s_mov_b32 vcc_lo, 0x141000
	v_lshl_add_u64 v[136:137], v[132:133], 0, vcc
	global_load_dwordx4 v[188:191], v[136:137], off
	s_mov_b32 vcc_lo, 0x142000
	v_lshl_add_u64 v[136:137], v[132:133], 0, vcc
	global_load_dwordx4 v[192:195], v[136:137], off
	s_mov_b32 vcc_lo, 0x15c000
	v_lshl_add_u64 v[136:137], v[132:133], 0, vcc
	global_load_dwordx4 v[196:199], v[136:137], off
	s_mov_b32 vcc_lo, 0x15d000
	v_lshl_add_u64 v[136:137], v[132:133], 0, vcc
	global_load_dwordx4 v[200:203], v[136:137], off
	s_mov_b32 vcc_lo, 0x177000
	v_lshl_add_u64 v[136:137], v[132:133], 0, vcc
	global_load_dwordx4 v[204:207], v[136:137], off
	s_mov_b32 vcc_lo, 0x178000
	v_lshl_add_u64 v[136:137], v[132:133], 0, vcc
	global_load_dwordx4 v[208:211], v[136:137], off
	s_mov_b32 vcc_lo, 0x192000
	v_lshl_add_u64 v[136:137], v[132:133], 0, vcc
	global_load_dwordx4 v[212:215], v[136:137], off
	s_mov_b32 vcc_lo, 0x193000
	v_lshl_add_u64 v[136:137], v[132:133], 0, vcc
	global_load_dwordx4 v[218:221], v[136:137], off
	s_mov_b32 vcc_lo, 0x1ad000
	v_lshl_add_u64 v[136:137], v[132:133], 0, vcc
	global_load_dwordx4 v[222:225], v[136:137], off
	s_mov_b32 vcc_lo, 0x1ae000
	v_lshl_add_u64 v[136:137], v[132:133], 0, vcc
	global_load_dwordx4 v[226:229], v[136:137], off
	s_waitcnt vmcnt(0)
	v_pk_add_f32 v[144:145], v[144:145], v[172:173]
	v_pk_add_f32 v[146:147], v[146:147], v[174:175]
	v_pk_add_f32 v[140:141], v[140:141], v[176:177]
	v_pk_add_f32 v[142:143], v[142:143], v[178:179]
	v_pk_add_f32 v[144:145], v[144:145], v[180:181]
	v_pk_add_f32 v[146:147], v[146:147], v[182:183]
	v_pk_add_f32 v[140:141], v[140:141], v[184:185]
	v_pk_add_f32 v[142:143], v[142:143], v[186:187]
	v_pk_add_f32 v[144:145], v[144:145], v[188:189]
	v_pk_add_f32 v[146:147], v[146:147], v[190:191]
	v_pk_add_f32 v[140:141], v[140:141], v[192:193]
	v_pk_add_f32 v[142:143], v[142:143], v[194:195]
	v_pk_add_f32 v[144:145], v[144:145], v[196:197]
	v_pk_add_f32 v[146:147], v[146:147], v[198:199]
	v_pk_add_f32 v[140:141], v[140:141], v[200:201]
	v_pk_add_f32 v[142:143], v[142:143], v[202:203]
	v_pk_add_f32 v[144:145], v[144:145], v[204:205]
	v_pk_add_f32 v[146:147], v[146:147], v[206:207]
	v_pk_add_f32 v[140:141], v[140:141], v[208:209]
	v_pk_add_f32 v[142:143], v[142:143], v[210:211]
	v_pk_add_f32 v[144:145], v[144:145], v[212:213]
	v_pk_add_f32 v[146:147], v[146:147], v[214:215]
	v_pk_add_f32 v[140:141], v[140:141], v[218:219]
	v_pk_add_f32 v[142:143], v[142:143], v[220:221]
	v_pk_add_f32 v[144:145], v[144:145], v[222:223]
	v_pk_add_f32 v[146:147], v[146:147], v[224:225]
	v_pk_add_f32 v[140:141], v[140:141], v[226:227]
	v_pk_add_f32 v[142:143], v[142:143], v[228:229]
	v_pk_add_f32 v[142:143], v[142:143], 1.0 op_sel_hi:[1,0]
	v_pk_add_f32 v[140:141], v[140:141], 1.0 op_sel_hi:[1,0]
	v_pk_mul_f32 v[132:133], v[170:171], v[142:143]
	v_pk_mul_f32 v[130:131], v[168:169], v[140:141]
	ds_write_b128 v135, v[130:133]
	ds_write_b128 v135, v[144:147] offset:4096
